# DSA row-norm phase: two rows prefetched ahead (alternating register sets)
# baseline (speedup 1.0000x reference)
.LBB0_1306:
	s_cmp_lt_i32 s62, 14
	s_cselect_b64 s[6:7], -1, 0
	s_cmp_gt_i32 s61, 13
	s_cselect_b64 s[8:9], -1, 0
	s_and_b64 s[6:7], s[6:7], s[8:9]
	s_mov_b64 s[12:13], 0
	s_andn2_b64 vcc, exec, s[6:7]
	s_mov_b64 s[16:17], 0
	s_cbranch_vccnz .LBB0_1366
	v_lshrrev_b32_e32 v0, 6, v192
	v_lshl_add_u32 v0, s2, 3, v0
	s_mov_b32 s3, 0x8000
	s_mov_b64 s[6:7], s[0:1]
	s_mov_b64 s[16:17], s[0:1]
	s_mov_b64 s[26:27], s[0:1]
	s_mov_b64 s[28:29], s[0:1]
	s_mov_b64 s[30:31], s[0:1]
	s_mov_b64 s[8:9], s[0:1]
	s_mov_b64 s[24:25], s[0:1]
	s_mov_b64 s[34:35], s[0:1]
	s_mov_b64 s[36:37], s[0:1]
	v_cmp_gt_i32_e32 vcc, s3, v0
	s_and_saveexec_b64 s[14:15], vcc
	s_cbranch_execz .LBB0_1312
	s_load_dwordx2 s[38:39], s[6:7], 0x100
	s_load_dwordx2 s[40:41], s[16:17], 0x100
	s_load_dwordx2 s[42:43], s[26:27], 0x100
	s_load_dwordx2 s[44:45], s[28:29], 0x100
	s_nop 0
	s_load_dwordx2 s[6:7], s[30:31], 0x100
	s_waitcnt lgkmcnt(0)
	s_add_u32 s16, s38, 0xc000000
	s_addc_u32 s17, s39, 0
	s_load_dwordx2 s[26:27], s[8:9], 0x90
	s_load_dwordx2 s[28:29], s[24:25], 0xa8
	s_load_dwordx2 s[30:31], s[34:35], 0xd0
	s_load_dwordx2 s[38:39], s[36:37], 0xd8
	v_and_b32_e32 v24, 63, v192
	v_mov_b32_e32 v3, 0
	v_lshlrev_b32_e32 v8, 3, v24
	v_mov_b32_e32 v9, v3
	v_lshlrev_b32_e32 v2, 2, v24
	v_lshl_add_u64 v[6:7], s[40:41], 0, v[8:9]
	s_mov_b64 s[8:9], 0x14000000
	v_lshlrev_b32_e32 v4, 4, v24
	v_mov_b32_e32 v5, v3
	v_lshl_add_u64 v[6:7], v[6:7], 0, s[8:9]
	v_lshlrev_b32_e32 v22, 1, v24
	v_mov_b32_e32 v23, v3
	v_lshl_add_u64 v[10:11], s[42:43], 0, v[2:3]
	s_mov_b64 s[8:9], 0x15000000
	s_waitcnt lgkmcnt(0)
	v_lshl_add_u64 v[4:5], s[26:27], 0, v[4:5]
	v_lshl_add_u64 v[10:11], v[10:11], 0, s[8:9]
	v_lshl_add_u64 v[16:17], s[44:45], 0, v[22:23]
	s_mov_b64 s[8:9], 0x15800000
	v_lshl_add_u64 v[18:19], s[6:7], 0, v[2:3]
	s_mov_b64 s[6:7], 0x15c00000
	s_mov_b32 s26, 0x3c800000
	v_lshl_add_u64 v[8:9], s[28:29], 0, v[8:9]
	v_lshl_add_u64 v[12:13], s[30:31], 0, v[2:3]
	v_lshl_add_u64 v[14:15], s[38:39], 0, v[2:3]
	v_lshl_add_u64 v[16:17], v[16:17], 0, s[8:9]
	v_cmp_gt_u32_e32 vcc, 16, v24
	v_lshl_add_u64 v[18:19], v[18:19], 0, s[6:7]
	s_lshl_b32 s3, s22, 3
	s_mov_b64 s[24:25], 0
	v_lshlrev_b32_e32 v2, 2, v2
	v_mov_b32_e32 v20, 0x358637bd
	s_mov_b32 s28, 0x800000
	v_lshlrev_b32_e32 v22, 2, v22
	v_lshlrev_b32_e32 v24, 2, v24
	v_mov_b32_e32 v25, v3
	s_brev_b32 s27, 60
	s_movk_i32 s29, 0x7fff
	global_load_dwordx4 v[44:47], v[4:5], off
	global_load_dwordx2 v[48:49], v[8:9], off
	global_load_dword v50, v[12:13], off
	global_load_dword v51, v[14:15], off
	s_lshl_b32 s95, s3, 1
	v_mov_b32_e32 v43, 0
	v_mov_b32_e32 v42, v0
	v_lshlrev_b64 v[64:65], 11, v[42:43]
	v_lshl_add_u64 v[64:65], s[16:17], 0, v[64:65]
	v_lshl_add_u64 v[66:67], v[64:65], 0, v[2:3]
	global_load_dwordx4 v[56:59], v[66:67], off
	v_lshl_add_u64 v[66:67], v[64:65], 0, v[22:23]
	global_load_dwordx2 v[60:61], v[66:67], off offset:1024
	v_lshl_add_u64 v[64:65], v[64:65], 0, v[24:25]
	global_load_dword v62, v[64:65], off offset:1536
	global_load_dword v63, v[64:65], off offset:1792
	v_add_u32_e32 v42, s3, v0
	v_min_u32_e32 v42, s29, v42
	v_lshlrev_b64 v[64:65], 11, v[42:43]
	v_lshl_add_u64 v[64:65], s[16:17], 0, v[64:65]
	v_lshl_add_u64 v[66:67], v[64:65], 0, v[2:3]
	global_load_dwordx4 v[68:71], v[66:67], off
	v_lshl_add_u64 v[66:67], v[64:65], 0, v[22:23]
	global_load_dwordx2 v[72:73], v[66:67], off offset:1024
	v_lshl_add_u64 v[64:65], v[64:65], 0, v[24:25]
	global_load_dword v74, v[64:65], off offset:1536
	global_load_dword v75, v[64:65], off offset:1792
	s_waitcnt vmcnt(0)
	s_branch .LBB0_1310

.LBB0_1310:
	s_waitcnt vmcnt(12)
	v_mov_b32_e32 v28, v56
	v_mov_b32_e32 v29, v57
	v_mov_b32_e32 v30, v58
	v_mov_b32_e32 v31, v59
	v_mov_b32_e32 v52, v60
	v_mov_b32_e32 v53, v61
	v_mov_b32_e32 v54, v62
	v_mov_b32_e32 v55, v63
	v_add_u32_e32 v42, s95, v0
	v_min_u32_e32 v42, s29, v42
	v_mov_b32_e32 v43, 0
	v_lshlrev_b64 v[64:65], 11, v[42:43]
	v_lshl_add_u64 v[64:65], s[16:17], 0, v[64:65]
	v_lshl_add_u64 v[66:67], v[64:65], 0, v[2:3]
	global_load_dwordx4 v[56:59], v[66:67], off
	v_lshl_add_u64 v[66:67], v[64:65], 0, v[22:23]
	global_load_dwordx2 v[60:61], v[66:67], off offset:1024
	v_lshl_add_u64 v[64:65], v[64:65], 0, v[24:25]
	global_load_dword v62, v[64:65], off offset:1536
	global_load_dword v63, v[64:65], off offset:1792
	v_ashrrev_i32_e32 v1, 31, v0
	v_lshlrev_b64 v[36:37], 9, v[0:1]
	v_lshl_add_u64 v[36:37], v[6:7], 0, v[36:37]
	v_mul_f32_e32 v21, v29, v29
	v_mul_f32_e32 v38, v31, v31
	v_fmac_f32_e32 v21, v28, v28
	v_fmac_f32_e32 v38, v30, v30
	v_add_f32_e32 v21, v21, v38
	s_nop 1
	v_add_f32_dpp v21, v21, v21 quad_perm:[1,0,3,2] row_mask:0xf bank_mask:0xf bound_ctrl:1
	s_nop 1
	v_add_f32_dpp v21, v21, v21 quad_perm:[2,3,0,1] row_mask:0xf bank_mask:0xf bound_ctrl:1
	s_nop 1
	v_add_f32_dpp v21, v21, v21 row_half_mirror row_mask:0xf bank_mask:0xf bound_ctrl:1
	s_nop 1
	v_add_f32_dpp v21, v21, v21 row_mirror row_mask:0xf bank_mask:0xf bound_ctrl:1
	v_mov_b32_e32 v38, v21
	s_nop 1
	v_permlane16_swap_b32_e32 v21, v38
	v_add_f32_e32 v21, v21, v38
	v_mov_b32_e32 v38, v21
	s_nop 1
	v_permlane32_swap_b32_e32 v21, v38
	v_add_f32_e32 v21, v21, v38
	v_fmamk_f32 v21, v21, 0x3b800000, v20
	v_mul_f32_e32 v38, 0x4b800000, v21
	v_cmp_gt_f32_e64 s[6:7], s28, v21
	s_nop 1
	v_cndmask_b32_e64 v21, v21, v38, s[6:7]
	v_rsq_f32_e32 v21, v21
	v_mul_f32_e32 v40, 0x45800000, v21
	v_cndmask_b32_e64 v40, v21, v40, s[6:7]
	v_mov_b32_e32 v21, v54
	v_pk_mul_f32 v[28:29], v[28:29], v[40:41] op_sel_hi:[1,0]
	v_pk_mul_f32 v[30:31], v[30:31], v[40:41] op_sel_hi:[1,0]
	v_pk_mul_f32 v[28:29], v[44:45], v[28:29]
	v_pk_mul_f32 v[30:31], v[46:47], v[30:31]
	v_cvt_pk_bf16_f32 v28, v28, v29
	v_cvt_pk_bf16_f32 v29, v30, v31
	global_store_dwordx2 v[36:37], v[28:29], off
	v_lshlrev_b64 v[32:33], 8, v[0:1]
	v_lshlrev_b64 v[34:35], 7, v[0:1]
	v_lshl_add_u64 v[32:33], v[10:11], 0, v[32:33]
	v_lshl_add_u64 v[34:35], v[16:17], 0, v[34:35]
	v_pk_mul_f32 v[36:37], v[52:53], v[52:53]
	v_add_f32_dpp v38, v21, v21 quad_perm:[1,0,3,2] row_mask:0xf bank_mask:0xf bound_ctrl:1
	v_add_f32_e32 v36, v36, v37
	s_nop 0
	v_add_f32_dpp v37, v38, v38 quad_perm:[2,3,0,1] row_mask:0xf bank_mask:0xf bound_ctrl:1
	v_add_f32_dpp v36, v36, v36 quad_perm:[1,0,3,2] row_mask:0xf bank_mask:0xf bound_ctrl:1
	s_nop 0
	v_add_f32_dpp v37, v37, v37 row_half_mirror row_mask:0xf bank_mask:0xf bound_ctrl:1
	v_add_f32_dpp v36, v36, v36 quad_perm:[2,3,0,1] row_mask:0xf bank_mask:0xf bound_ctrl:1
	s_nop 0
	v_add_f32_dpp v37, v37, v37 row_mirror row_mask:0xf bank_mask:0xf bound_ctrl:1
	v_mov_b32_e32 v38, v37
	v_add_f32_dpp v36, v36, v36 row_half_mirror row_mask:0xf bank_mask:0xf bound_ctrl:1
	s_nop 0
	v_permlane16_swap_b32_e32 v37, v38
	v_add_f32_dpp v36, v36, v36 row_mirror row_mask:0xf bank_mask:0xf bound_ctrl:1
	v_add_f32_e32 v38, v37, v38
	v_mov_b32_e32 v39, v36
	v_mov_b32_e32 v42, v38
	s_nop 0
	v_permlane16_swap_b32_e32 v36, v39
	v_permlane32_swap_b32_e32 v38, v42
	v_add_f32_e32 v37, v36, v39
	v_add_f32_e32 v36, v38, v42
	v_fmac_f32_e32 v21, 0xbc800000, v36
	v_mul_f32_e32 v36, v21, v21
	v_mov_b32_e32 v39, v37
	s_nop 1
	v_permlane32_swap_b32_e32 v37, v39
	v_mov_b32_dpp v36, v36 quad_perm:[1,0,3,2] row_mask:0xf bank_mask:0xf bound_ctrl:1
	v_fmac_f32_e32 v36, v21, v21
	s_nop 1
	v_add_f32_dpp v36, v36, v36 quad_perm:[2,3,0,1] row_mask:0xf bank_mask:0xf bound_ctrl:1
	s_nop 1
	v_add_f32_dpp v36, v36, v36 row_half_mirror row_mask:0xf bank_mask:0xf bound_ctrl:1
	s_nop 1
	v_add_f32_dpp v36, v36, v36 row_mirror row_mask:0xf bank_mask:0xf bound_ctrl:1
	v_mov_b32_e32 v38, v36
	s_nop 1
	v_permlane16_swap_b32_e32 v36, v38
	v_add_f32_e32 v36, v36, v38
	v_mov_b32_e32 v38, v36
	s_nop 1
	v_permlane32_swap_b32_e32 v36, v38
	v_pk_add_f32 v[36:37], v[36:37], v[38:39]
	s_nop 0
	v_pk_fma_f32 v[36:37], v[36:37], s[26:27], v[20:21] op_sel_hi:[1,1,0]
	s_nop 0
	v_mul_f32_e32 v38, 0x4b800000, v37
	v_mul_f32_e32 v39, 0x4b800000, v36
	v_cmp_gt_f32_e64 s[6:7], s28, v37
	v_cmp_gt_f32_e64 s[8:9], s28, v36
	s_nop 0
	v_cndmask_b32_e64 v37, v37, v38, s[6:7]
	v_cndmask_b32_e64 v36, v36, v39, s[8:9]
	v_rsq_f32_e32 v37, v37
	v_rsq_f32_e32 v38, v36
	v_mul_f32_e32 v36, 0x45800000, v37
	v_mul_f32_e32 v39, 0x45800000, v38
	v_cndmask_b32_e64 v36, v37, v36, s[6:7]
	v_cndmask_b32_e64 v37, v38, v39, s[8:9]
	v_pk_mul_f32 v[28:29], v[52:53], v[36:37] op_sel_hi:[1,0]
	v_mul_f32_e32 v21, v21, v37
	v_pk_mul_f32 v[28:29], v[48:49], v[28:29]
	v_fma_f32 v41, v50, v21, v51
	v_cvt_pk_bf16_f32 v21, v28, v29
	v_cvt_pk_bf16_f32 v28, v41, s0
	global_store_dword v[32:33], v21, off
	global_store_short v[34:35], v28, off
	s_and_saveexec_b64 s[6:7], vcc
	s_cbranch_execz .Ld2_c1
	v_lshlrev_b64 v[26:27], 6, v[0:1]
	v_lshl_add_u64 v[26:27], v[18:19], 0, v[26:27]
	v_mul_f32_e32 v1, 0x3d000000, v55
	global_store_dword v[26:27], v1, off
	s_branch .Ld2_c1
.Ld2_c1:
	s_or_b64 exec, exec, s[6:7]
	v_add_u32_e32 v0, s3, v0
	v_cmp_lt_i32_e64 s[6:7], s29, v0
	s_or_b64 s[24:25], s[6:7], s[24:25]
	s_andn2_b64 exec, exec, s[24:25]
	s_cbranch_execz .LBB0_1312
	s_waitcnt vmcnt(12)
	v_mov_b32_e32 v28, v68
	v_mov_b32_e32 v29, v69
	v_mov_b32_e32 v30, v70
	v_mov_b32_e32 v31, v71
	v_mov_b32_e32 v52, v72
	v_mov_b32_e32 v53, v73
	v_mov_b32_e32 v54, v74
	v_mov_b32_e32 v55, v75
	v_add_u32_e32 v42, s95, v0
	v_min_u32_e32 v42, s29, v42
	v_mov_b32_e32 v43, 0
	v_lshlrev_b64 v[64:65], 11, v[42:43]
	v_lshl_add_u64 v[64:65], s[16:17], 0, v[64:65]
	v_lshl_add_u64 v[66:67], v[64:65], 0, v[2:3]
	global_load_dwordx4 v[68:71], v[66:67], off
	v_lshl_add_u64 v[66:67], v[64:65], 0, v[22:23]
	global_load_dwordx2 v[72:73], v[66:67], off offset:1024
	v_lshl_add_u64 v[64:65], v[64:65], 0, v[24:25]
	global_load_dword v74, v[64:65], off offset:1536
	global_load_dword v75, v[64:65], off offset:1792
	v_ashrrev_i32_e32 v1, 31, v0
	v_lshlrev_b64 v[36:37], 9, v[0:1]
	v_lshl_add_u64 v[36:37], v[6:7], 0, v[36:37]
	v_mul_f32_e32 v21, v29, v29
	v_mul_f32_e32 v38, v31, v31
	v_fmac_f32_e32 v21, v28, v28
	v_fmac_f32_e32 v38, v30, v30
	v_add_f32_e32 v21, v21, v38
	s_nop 1
	v_add_f32_dpp v21, v21, v21 quad_perm:[1,0,3,2] row_mask:0xf bank_mask:0xf bound_ctrl:1
	s_nop 1
	v_add_f32_dpp v21, v21, v21 quad_perm:[2,3,0,1] row_mask:0xf bank_mask:0xf bound_ctrl:1
	s_nop 1
	v_add_f32_dpp v21, v21, v21 row_half_mirror row_mask:0xf bank_mask:0xf bound_ctrl:1
	s_nop 1
	v_add_f32_dpp v21, v21, v21 row_mirror row_mask:0xf bank_mask:0xf bound_ctrl:1
	v_mov_b32_e32 v38, v21
	s_nop 1
	v_permlane16_swap_b32_e32 v21, v38
	v_add_f32_e32 v21, v21, v38
	v_mov_b32_e32 v38, v21
	s_nop 1
	v_permlane32_swap_b32_e32 v21, v38
	v_add_f32_e32 v21, v21, v38
	v_fmamk_f32 v21, v21, 0x3b800000, v20
	v_mul_f32_e32 v38, 0x4b800000, v21
	v_cmp_gt_f32_e64 s[6:7], s28, v21
	s_nop 1
	v_cndmask_b32_e64 v21, v21, v38, s[6:7]
	v_rsq_f32_e32 v21, v21
	v_mul_f32_e32 v40, 0x45800000, v21
	v_cndmask_b32_e64 v40, v21, v40, s[6:7]
	v_mov_b32_e32 v21, v54
	v_pk_mul_f32 v[28:29], v[28:29], v[40:41] op_sel_hi:[1,0]
	v_pk_mul_f32 v[30:31], v[30:31], v[40:41] op_sel_hi:[1,0]
	v_pk_mul_f32 v[28:29], v[44:45], v[28:29]
	v_pk_mul_f32 v[30:31], v[46:47], v[30:31]
	v_cvt_pk_bf16_f32 v28, v28, v29
	v_cvt_pk_bf16_f32 v29, v30, v31
	global_store_dwordx2 v[36:37], v[28:29], off
	v_lshlrev_b64 v[32:33], 8, v[0:1]
	v_lshlrev_b64 v[34:35], 7, v[0:1]
	v_lshl_add_u64 v[32:33], v[10:11], 0, v[32:33]
	v_lshl_add_u64 v[34:35], v[16:17], 0, v[34:35]
	v_pk_mul_f32 v[36:37], v[52:53], v[52:53]
	v_add_f32_dpp v38, v21, v21 quad_perm:[1,0,3,2] row_mask:0xf bank_mask:0xf bound_ctrl:1
	v_add_f32_e32 v36, v36, v37
	s_nop 0
	v_add_f32_dpp v37, v38, v38 quad_perm:[2,3,0,1] row_mask:0xf bank_mask:0xf bound_ctrl:1
	v_add_f32_dpp v36, v36, v36 quad_perm:[1,0,3,2] row_mask:0xf bank_mask:0xf bound_ctrl:1
	s_nop 0
	v_add_f32_dpp v37, v37, v37 row_half_mirror row_mask:0xf bank_mask:0xf bound_ctrl:1
	v_add_f32_dpp v36, v36, v36 quad_perm:[2,3,0,1] row_mask:0xf bank_mask:0xf bound_ctrl:1
	s_nop 0
	v_add_f32_dpp v37, v37, v37 row_mirror row_mask:0xf bank_mask:0xf bound_ctrl:1
	v_mov_b32_e32 v38, v37
	v_add_f32_dpp v36, v36, v36 row_half_mirror row_mask:0xf bank_mask:0xf bound_ctrl:1
	s_nop 0
	v_permlane16_swap_b32_e32 v37, v38
	v_add_f32_dpp v36, v36, v36 row_mirror row_mask:0xf bank_mask:0xf bound_ctrl:1
	v_add_f32_e32 v38, v37, v38
	v_mov_b32_e32 v39, v36
	v_mov_b32_e32 v42, v38
	s_nop 0
	v_permlane16_swap_b32_e32 v36, v39
	v_permlane32_swap_b32_e32 v38, v42
	v_add_f32_e32 v37, v36, v39
	v_add_f32_e32 v36, v38, v42
	v_fmac_f32_e32 v21, 0xbc800000, v36
	v_mul_f32_e32 v36, v21, v21
	v_mov_b32_e32 v39, v37
	s_nop 1
	v_permlane32_swap_b32_e32 v37, v39
	v_mov_b32_dpp v36, v36 quad_perm:[1,0,3,2] row_mask:0xf bank_mask:0xf bound_ctrl:1
	v_fmac_f32_e32 v36, v21, v21
	s_nop 1
	v_add_f32_dpp v36, v36, v36 quad_perm:[2,3,0,1] row_mask:0xf bank_mask:0xf bound_ctrl:1
	s_nop 1
	v_add_f32_dpp v36, v36, v36 row_half_mirror row_mask:0xf bank_mask:0xf bound_ctrl:1
	s_nop 1
	v_add_f32_dpp v36, v36, v36 row_mirror row_mask:0xf bank_mask:0xf bound_ctrl:1
	v_mov_b32_e32 v38, v36
	s_nop 1
	v_permlane16_swap_b32_e32 v36, v38
	v_add_f32_e32 v36, v36, v38
	v_mov_b32_e32 v38, v36
	s_nop 1
	v_permlane32_swap_b32_e32 v36, v38
	v_pk_add_f32 v[36:37], v[36:37], v[38:39]
	s_nop 0
	v_pk_fma_f32 v[36:37], v[36:37], s[26:27], v[20:21] op_sel_hi:[1,1,0]
	s_nop 0
	v_mul_f32_e32 v38, 0x4b800000, v37
	v_mul_f32_e32 v39, 0x4b800000, v36
	v_cmp_gt_f32_e64 s[6:7], s28, v37
	v_cmp_gt_f32_e64 s[8:9], s28, v36
	s_nop 0
	v_cndmask_b32_e64 v37, v37, v38, s[6:7]
	v_cndmask_b32_e64 v36, v36, v39, s[8:9]
	v_rsq_f32_e32 v37, v37
	v_rsq_f32_e32 v38, v36
	v_mul_f32_e32 v36, 0x45800000, v37
	v_mul_f32_e32 v39, 0x45800000, v38
	v_cndmask_b32_e64 v36, v37, v36, s[6:7]
	v_cndmask_b32_e64 v37, v38, v39, s[8:9]
	v_pk_mul_f32 v[28:29], v[52:53], v[36:37] op_sel_hi:[1,0]
	v_mul_f32_e32 v21, v21, v37
	v_pk_mul_f32 v[28:29], v[48:49], v[28:29]
	v_fma_f32 v41, v50, v21, v51
	v_cvt_pk_bf16_f32 v21, v28, v29
	v_cvt_pk_bf16_f32 v28, v41, s0
	global_store_dword v[32:33], v21, off
	global_store_short v[34:35], v28, off
	s_and_saveexec_b64 s[6:7], vcc
	s_cbranch_execz .LBB0_1309
	v_lshlrev_b64 v[26:27], 6, v[0:1]
	v_lshl_add_u64 v[26:27], v[18:19], 0, v[26:27]
	v_mul_f32_e32 v1, 0x3d000000, v55
	global_store_dword v[26:27], v1, off
	s_branch .LBB0_1309
